# gdn_prep block forward-substitution stage: LDS operand reads hoisted ahead of the MFMA chain (two groups), waits re-derived
# baseline (speedup 1.0000x reference)
; DI void gdn_prep_unit(const Params& P, int h, int n, unsigned char* lds, int tid, u32x4 (&raw)[12], float& sbv, float& sav, int unext, bool cw_lds = false) {
;     ...
;     { const int l15 = lane & 15, g = lane >> 4;
;       u32x2 xh[4];
; #pragma unroll
;       for (int b = 0; b < 4; ++b) {
;           float* xp = X + (16 * b + 4 * g) * 132 + 16 * wave + l15;
;           f32x4 acc = {xp[0], xp[132], xp[264], xp[396]};
; #pragma unroll
;           for (int bp = 0; bp < b; bp += 2) {
;               const f32x4 a0 = *(const f32x4*)(Ml + (16 * b + l15) * 68 + 16 * bp + 4 * g);
;               f32x4 a1 = {0.f, 0.f, 0.f, 0.f}; u32x2 x1 = {0u, 0u};
;               if (bp + 1 < b) { a1 = *(const f32x4*)(Ml + (16 * b + l15) * 68 + 16 * (bp + 1) + 4 * g); x1 = xh[bp + 1]; }
;               u32x4 ap; ap.x = pk2(-a0[0], -a0[1]); ap.y = pk2(-a0[2], -a0[3]); ap.z = pk2(-a1[0], -a1[1]); ap.w = pk2(-a1[2], -a1[3]);
;               u32x4 bpk; bpk.x = xh[bp].x; bpk.y = xh[bp].y; bpk.z = x1.x; bpk.w = x1.y;
;               acc = MFMA16(__builtin_bit_cast(bf16x8, ap), __builtin_bit_cast(bf16x8, bpk), acc); }
;           const f32x4 tt = *(const f32x4*)(Tl + (16 * b + l15) * 20 + 4 * g);
;           f32x4 xb = {0.f, 0.f, 0.f, 0.f};
;           { u32x4 tp; tp.x = pk2(tt[0], tt[1]); tp.y = pk2(tt[2], tt[3]); tp.z = 0u; tp.w = 0u;
;             u32x4 rp; rp.x = pk2(acc[0], acc[1]); rp.y = pk2(acc[2], acc[3]); rp.z = 0u; rp.w = 0u;
;             xb = MFMA16(__builtin_bit_cast(bf16x8, tp), __builtin_bit_cast(bf16x8, rp), xb); }
;           xh[b].x = pk2(xb[0], xb[1]); xh[b].y = pk2(xb[2], xb[3]);
;           xp[0] = xb[0]; xp[132] = xb[1]; xp[264] = xb[2]; xp[396] = xb[3];
;       } }
;     PREP_BAR();
;     { bf16_t* WB = (bf16_t*)(ws + WS_WB) + (size_t)unit * 4096;
; #pragma unroll
;       for (int k = 0; k < 2; ++k) { const int gidx = tid + 512 * k, cgi = gidx >> 8, mb = (gidx >> 6) & 3, l = gidx & 63;
;           const float* xp = X + (16 * mb + 4 * (l >> 4)) * 132 + 16 * cgi + (l & 15);
;           u32x2 o; o.x = pk2(xp[0], xp[132]); o.y = pk2(xp[264], xp[396]); *(u32x2*)(WB + gidx * 4) = o; }
;       const int c = tid >> 3, pg = tid & 7, s = pg >> 2, g = pg & 3;
;       float v[8];
; #pragma unroll
;       for (int j = 0; j < 8; ++j) { const int d = 32 * s + 16 * (j >> 2) + 4 * g + (j & 3); v[j] = -X[c * 132 + 64 + d]; }
.LBB0_491:
	s_or_b64 exec, exec, s[0:1]
	s_waitcnt lgkmcnt(0)
	s_barrier
	v_add_u32_e32 v104, 0x8c00, v215
	ds_read2_b32 v[222:223], v104 offset1:132
	v_add_u32_e32 v105, 0x9000, v215
	ds_read2_b32 v[224:225], v105 offset0:8 offset1:140
	ds_read_b128 v[226:229], v216
	v_add_u32_e32 v106, 0xac00, v215
	ds_read2_b32 v[230:231], v106 offset0:64 offset1:196
	v_add_u32_e32 v107, 0xb000, v215
	ds_read2_b32 v[232:233], v107 offset0:72 offset1:204
	ds_read_b128 v[234:237], v207 offset:18432
	ds_read_b128 v[240:243], v216 offset:1280
	v_add_u32_e32 v62, 0x8c00, v215
	v_add_u32_e32 v63, 0x9000, v215
	v_add_u32_e32 v66, 0xac00, v215
	v_add_u32_e32 v67, 0xb000, v215
	s_mov_b32 s79, s78
	s_waitcnt lgkmcnt(6)
	v_cvt_pk_bf16_f32 v58, v222, v223
	s_waitcnt lgkmcnt(4)
	v_cvt_pk_bf16_f32 v52, v226, v227
	v_cvt_pk_bf16_f32 v53, v228, v229
	v_mov_b32_e32 v54, v42
	v_mov_b32_e32 v55, v42
	v_cvt_pk_bf16_f32 v59, v224, v225
	v_mov_b32_e32 v60, v42
	v_mov_b32_e32 v61, v42
	v_add_u32_e32 v70, 0xce00, v215
	v_add_u32_e32 v71, 0xd200, v215
	v_mfma_f32_16x16x32_bf16 v[58:61], v[52:55], v[58:61], 0
	s_nop 7
	ds_write2_b32 v62, v58, v59 offset1:132
	ds_write2_b32 v63, v60, v61 offset0:8 offset1:140
	v_cvt_pk_bf16_f32 v52, v58, v59
	v_cvt_pk_bf16_f32 v53, v60, v61
	v_add_u32_e32 v72, 0xee00, v215
	v_add_u32_e32 v73, 0xf200, v215
	s_movk_i32 s0, 0x1000
	s_add_u32 s96, s96, 0x8000
	s_waitcnt lgkmcnt(3)
	v_xor_b32_e32 v54, 0x80000000, v235
	v_xor_b32_e32 v55, 0x80000000, v234
	v_cvt_pk_bf16_f32 v54, v55, v54
	v_xor_b32_e32 v55, 0x80000000, v236
	v_xor_b32_e32 v62, 0x80000000, v237
	v_cvt_pk_bf16_f32 v55, v55, v62
	v_mov_b64_e32 v[62:63], s[76:77]
	v_mov_b64_e32 v[64:65], s[78:79]
	v_mov_b32_e32 v62, v54
	v_mov_b32_e32 v63, v55
	v_mov_b32_e32 v54, v42
	v_mov_b32_e32 v55, v42
	s_addc_u32 s97, s97, 0
	s_add_i32 s3, s3, 8
	v_mfma_f32_16x16x32_bf16 v[58:61], v[62:65], v[52:55], v[230:233]
	s_add_u32 s4, s4, 4
	s_addc_u32 s5, s5, 0
	s_cmp_eq_u32 s96, 0x40000
	s_waitcnt lgkmcnt(2)
	v_cvt_pk_bf16_f32 v62, v240, v241
	v_cvt_pk_bf16_f32 v63, v242, v243
	v_mov_b32_e32 v64, v42
	v_mov_b32_e32 v65, v42
	v_cvt_pk_bf16_f32 v58, v58, v59
	v_cvt_pk_bf16_f32 v59, v60, v61
	v_mov_b32_e32 v60, v42
	v_mov_b32_e32 v61, v42
	s_nop 1
	v_mfma_f32_16x16x32_bf16 v[58:61], v[62:65], v[58:61], 0
	s_nop 7
	ds_write2_b32 v66, v58, v59 offset0:64 offset1:196
	ds_write2_b32 v67, v60, v61 offset0:72 offset1:204
	v_cvt_pk_bf16_f32 v54, v58, v59
	v_cvt_pk_bf16_f32 v55, v60, v61
	ds_read2_b32 v[222:223], v70 offset1:132
	ds_read2_b32 v[224:225], v71 offset0:8 offset1:140
	ds_read_b128 v[226:229], v208 offset:18432
	ds_read_b128 v[230:233], v208 offset:18496
	ds_read_b128 v[234:237], v216 offset:2560
	ds_read2_b32 v[240:241], v72 offset0:64 offset1:196
	ds_read2_b32 v[242:243], v73 offset0:72 offset1:204
	ds_read_b128 v[244:247], v209 offset:18432
	ds_read_b128 v[248:251], v209 offset:18496
	ds_read_b128 v[252:255], v209 offset:18560
	ds_read_b128 v[100:103], v216 offset:3840
	s_waitcnt lgkmcnt(8)
	v_xor_b32_e32 v63, 0x80000000, v227
	v_xor_b32_e32 v62, 0x80000000, v226
	v_cvt_pk_bf16_f32 v62, v62, v63
	v_xor_b32_e32 v63, 0x80000000, v228
	v_xor_b32_e32 v64, 0x80000000, v229
	v_cvt_pk_bf16_f32 v63, v63, v64
	s_waitcnt lgkmcnt(7)
	v_xor_b32_e32 v64, 0x80000000, v231
	v_xor_b32_e32 v65, 0x80000000, v230
	v_cvt_pk_bf16_f32 v64, v65, v64
	v_xor_b32_e32 v65, 0x80000000, v232
	v_xor_b32_e32 v66, 0x80000000, v233
	v_cvt_pk_bf16_f32 v65, v65, v66
	s_nop 1
	v_mfma_f32_16x16x32_bf16 v[58:61], v[62:65], v[52:55], v[222:225]
	s_waitcnt lgkmcnt(6)
	v_cvt_pk_bf16_f32 v62, v234, v235
	v_cvt_pk_bf16_f32 v63, v236, v237
	v_mov_b32_e32 v64, v42
	v_mov_b32_e32 v65, v42
	s_nop 1
	s_nop 0
	v_cvt_pk_bf16_f32 v58, v58, v59
	v_cvt_pk_bf16_f32 v59, v60, v61
	v_mov_b32_e32 v60, v42
	v_mov_b32_e32 v61, v42
	s_nop 1
	v_mfma_f32_16x16x32_bf16 v[58:61], v[62:65], v[58:61], 0
	s_nop 7
	ds_write2_b32 v70, v58, v59 offset1:132
	ds_write2_b32 v71, v60, v61 offset0:8 offset1:140
	v_cvt_pk_bf16_f32 v62, v58, v59
	v_cvt_pk_bf16_f32 v63, v60, v61
	s_waitcnt lgkmcnt(5)
	v_xor_b32_e32 v65, 0x80000000, v245
	v_xor_b32_e32 v64, 0x80000000, v244
	v_cvt_pk_bf16_f32 v64, v64, v65
	v_xor_b32_e32 v65, 0x80000000, v246
	v_xor_b32_e32 v66, 0x80000000, v247
	v_cvt_pk_bf16_f32 v65, v65, v66
	s_waitcnt lgkmcnt(4)
	v_xor_b32_e32 v66, 0x80000000, v249
	v_xor_b32_e32 v67, 0x80000000, v248
	v_cvt_pk_bf16_f32 v66, v67, v66
	v_xor_b32_e32 v67, 0x80000000, v250
	v_xor_b32_e32 v68, 0x80000000, v251
	v_cvt_pk_bf16_f32 v67, v67, v68
	s_nop 1
	v_mfma_f32_16x16x32_bf16 v[52:55], v[64:67], v[52:55], v[240:243]
	s_nop 2
	s_waitcnt lgkmcnt(3)
	v_xor_b32_e32 v59, 0x80000000, v253
	v_xor_b32_e32 v58, 0x80000000, v252
	v_cvt_pk_bf16_f32 v64, v58, v59
	v_xor_b32_e32 v58, 0x80000000, v254
	v_xor_b32_e32 v59, 0x80000000, v255
	v_cvt_pk_bf16_f32 v65, v58, v59
	v_mov_b64_e32 v[58:59], s[76:77]
	v_mov_b64_e32 v[60:61], s[78:79]
	v_mov_b32_e32 v58, v64
	v_mov_b32_e32 v59, v65
	v_mov_b32_e32 v64, v42
	v_mov_b32_e32 v65, v42
	s_nop 1
	v_mfma_f32_16x16x32_bf16 v[52:55], v[58:61], v[62:65], v[52:55]
	s_waitcnt lgkmcnt(2)
	v_cvt_pk_bf16_f32 v58, v100, v101
	v_cvt_pk_bf16_f32 v59, v102, v103
	v_mov_b32_e32 v60, v42
	v_mov_b32_e32 v61, v42
	s_nop 1
	s_nop 0
	v_cvt_pk_bf16_f32 v52, v52, v53
	v_cvt_pk_bf16_f32 v53, v54, v55
	v_mov_b32_e32 v54, v42
	v_mov_b32_e32 v55, v42
	s_nop 1
	v_mfma_f32_16x16x32_bf16 v[52:55], v[58:61], v[52:55], 0
	s_nop 7
	ds_write2_b32 v72, v52, v53 offset0:64 offset1:196
	ds_write2_b32 v73, v54, v55 offset0:72 offset1:204
	s_waitcnt lgkmcnt(0)
	s_barrier
	v_add_u32_e32 v52, 0x8c00, v210
	ds_read2_b32 v[52:53], v52 offset1:132
	v_add_u32_e32 v58, 0x8d40, v212
	v_add_u32_e32 v60, 0x8d48, v212
	ds_read2_b32 v[58:59], v58 offset1:1
	ds_read2_b32 v[60:61], v60 offset1:1
	s_waitcnt lgkmcnt(2)
	v_cvt_pk_bf16_f32 v52, v52, v53
	v_add_u32_e32 v53, 0x9000, v210
	ds_read2_b32 v[54:55], v53 offset0:8 offset1:140
	s_waitcnt lgkmcnt(0)
	v_cvt_pk_bf16_f32 v53, v54, v55
	global_store_dwordx2 v[86:87], v[52:53], off
	v_add_u32_e32 v52, 0x8c00, v211
	ds_read2_b32 v[52:53], v52 offset1:132
	s_waitcnt lgkmcnt(0)
	v_cvt_pk_bf16_f32 v52, v52, v53
	v_add_u32_e32 v53, 0x9000, v211
	ds_read2_b32 v[54:55], v53 offset0:8 offset1:140
	s_waitcnt lgkmcnt(0)
	v_cvt_pk_bf16_f32 v53, v54, v55
	v_add_co_u32_e32 v54, vcc, s0, v86
	s_nop 1
	v_addc_co_u32_e32 v55, vcc, 0, v87, vcc
	global_store_dwordx2 v[54:55], v[52:53], off
	ds_read_b128 v[52:55], v212 offset:36096
	v_lshl_add_u64 v[86:87], v[86:87], 0, s[84:85]
	s_waitcnt lgkmcnt(0)
	v_pk_add_f32 v[52:53], v[52:53], 0 neg_lo:[1,1] neg_hi:[1,1]
	v_pk_add_f32 v[54:55], v[54:55], 0 neg_lo:[1,1] neg_hi:[1,1]
	v_cvt_pk_bf16_f32 v52, v52, v53
	v_cvt_pk_bf16_f32 v53, v54, v55
	v_pk_add_f32 v[54:55], v[58:59], 0 neg_lo:[1,1] neg_hi:[1,1]
	v_pk_add_f32 v[58:59], v[60:61], 0 neg_lo:[1,1] neg_hi:[1,1]
	v_cvt_pk_bf16_f32 v54, v54, v55
	v_cvt_pk_bf16_f32 v55, v58, v59
	global_store_dwordx4 v[56:57], v[52:55], off
	s_cbranch_scc1 .LBB0_576
